# ffup epilogue: the reciprocal refinement without the two v_div_scale ops and the vcc-conditional fmas (no-ops for denominators 1+exp(.) below 2^96; v_div_fixup kept; identical bits otherwise)
# speedup vs baseline: 1.0038x; 1.0038x over previous
.LBB0_1034:
	v_lshl_or_b32 v115, v183, 3, v191
	v_lshrrev_b32_e32 v116, 6, v115
	v_and_b32_e32 v117, 63, v115
	v_lshlrev_b32_e32 v113, 11, v116
	v_add_u32_e32 v113, 0x10000, v113
	v_readfirstlane_b32 s100, v116
	v_and_b32_e32 v112, 31, v117
	v_lshl_add_u32 v112, v112, 1, v113
	v_lshrrev_b32_e32 v116, 5, v117
	v_lshl_add_u32 v112, v116, 8, v112
	v_lshl_add_u32 v113, v117, 4, v113
	v_lshrrev_b32_e32 v116, 2, v117
	v_mul_u32_u24_e32 v116, 0x1600, v116
	v_and_b32_e32 v114, 3, v117
	v_lshl_add_u32 v114, v114, 4, v116
	s_lshr_b32 s101, s100, 1
	s_lshl_b32 s101, s101, 6
	s_add_u32 s101, s101, s48
	s_mul_i32 s101, s101, 0x1600
	s_and_b32 s100, s100, 1
	s_lshl_b32 s100, s100, 6
	s_add_u32 s100, s100, s49
	s_add_u32 s101, s101, s100
	s_add_u32 s98, s90, 0x3971900
	s_addc_u32 s99, s91, 0
	s_add_u32 s98, s98, s101
	s_addc_u32 s99, s99, 0
	v_mul_f32_e32 v64, 0xbfb8aa3b, v48
	v_mul_f32_e32 v70, 0xbfb8aa3b, v49
	v_mul_f32_e32 v76, 0xbfb8aa3b, v50
	v_mul_f32_e32 v82, 0xbfb8aa3b, v51
	v_exp_f32_e32 v64, v64
	v_exp_f32_e32 v70, v70
	v_exp_f32_e32 v76, v76
	v_exp_f32_e32 v82, v82
	v_add_f32_e32 v64, 1.0, v64
	v_add_f32_e32 v70, 1.0, v70
	v_add_f32_e32 v76, 1.0, v76
	v_add_f32_e32 v82, 1.0, v82
	v_rcp_f32_e32 v66, v64
	v_rcp_f32_e32 v72, v70
	v_rcp_f32_e32 v78, v76
	v_rcp_f32_e32 v84, v82
	v_fma_f32 v69, -v64, v66, 1.0
	v_fma_f32 v75, -v70, v72, 1.0
	v_fma_f32 v81, -v76, v78, 1.0
	v_fma_f32 v87, -v82, v84, 1.0
	v_fmac_f32_e32 v66, v69, v66
	v_fmac_f32_e32 v72, v75, v72
	v_fmac_f32_e32 v78, v81, v78
	v_fmac_f32_e32 v84, v87, v84
	v_fma_f32 v69, -v64, v66, 1.0
	v_mul_f32_e32 v88, 0xbfb8aa3b, v52
	v_fma_f32 v75, -v70, v72, 1.0
	v_mul_f32_e32 v94, 0xbfb8aa3b, v53
	v_fma_f32 v81, -v76, v78, 1.0
	v_mul_f32_e32 v100, 0xbfb8aa3b, v54
	v_fma_f32 v87, -v82, v84, 1.0
	v_mul_f32_e32 v106, 0xbfb8aa3b, v55
	v_fma_f32 v68, v69, v66, v66
	v_exp_f32_e32 v88, v88
	v_fma_f32 v74, v75, v72, v72
	v_exp_f32_e32 v94, v94
	v_fma_f32 v80, v81, v78, v78
	v_exp_f32_e32 v100, v100
	v_fma_f32 v86, v87, v84, v84
	v_exp_f32_e32 v106, v106
	v_fma_f32 v69, -v64, v68, 1.0
	v_add_f32_e32 v88, 1.0, v88
	v_fma_f32 v75, -v70, v74, 1.0
	v_add_f32_e32 v94, 1.0, v94
	v_fma_f32 v81, -v76, v80, 1.0
	v_add_f32_e32 v100, 1.0, v100
	v_fma_f32 v87, -v82, v86, 1.0
	v_add_f32_e32 v106, 1.0, v106
	v_fma_f32 v65, v69, v66, v68
	v_rcp_f32_e32 v90, v88
	v_fma_f32 v71, v75, v72, v74
	v_rcp_f32_e32 v96, v94
	v_fma_f32 v77, v81, v78, v80
	v_rcp_f32_e32 v102, v100
	v_fma_f32 v83, v87, v84, v86
	v_rcp_f32_e32 v108, v106
	v_fma_f32 v93, -v88, v90, 1.0
	v_fma_f32 v99, -v94, v96, 1.0
	v_fma_f32 v105, -v100, v102, 1.0
	v_fma_f32 v111, -v106, v108, 1.0
	v_fmac_f32_e32 v90, v93, v90
	v_fmac_f32_e32 v96, v99, v96
	v_fmac_f32_e32 v102, v105, v102
	v_fmac_f32_e32 v108, v111, v108
	v_div_fixup_f32 v65, v65, v64, 1.0
	v_div_fixup_f32 v71, v71, v70, 1.0
	v_div_fixup_f32 v77, v77, v76, 1.0
	v_div_fixup_f32 v83, v83, v82, 1.0
	v_mul_f32_e32 v65, v48, v65
	v_mul_f32_e32 v71, v49, v71
	v_mul_f32_e32 v77, v50, v77
	v_mul_f32_e32 v83, v51, v83
	v_mul_f32_e32 v65, v32, v65
	v_mul_f32_e32 v71, v33, v71
	v_mul_f32_e32 v77, v34, v77
	v_mul_f32_e32 v83, v35, v83
	v_cvt_pk_bf16_f32 v65, v65, v65
	v_cvt_pk_bf16_f32 v71, v71, v71
	v_cvt_pk_bf16_f32 v77, v77, v77
	v_cvt_pk_bf16_f32 v83, v83, v83
	ds_write_b16 v112, v65
	ds_write_b16 v112, v71 offset:64
	ds_write_b16 v112, v77 offset:128
	ds_write_b16 v112, v83 offset:192
	v_fma_f32 v93, -v88, v90, 1.0
	v_mul_f32_e32 v64, 0xbfb8aa3b, v56
	v_fma_f32 v99, -v94, v96, 1.0
	v_mul_f32_e32 v70, 0xbfb8aa3b, v57
	v_fma_f32 v105, -v100, v102, 1.0
	v_mul_f32_e32 v76, 0xbfb8aa3b, v58
	v_fma_f32 v111, -v106, v108, 1.0
	v_mul_f32_e32 v82, 0xbfb8aa3b, v59
	v_fma_f32 v92, v93, v90, v90
	v_exp_f32_e32 v64, v64
	v_fma_f32 v98, v99, v96, v96
	v_exp_f32_e32 v70, v70
	v_fma_f32 v104, v105, v102, v102
	v_exp_f32_e32 v76, v76
	v_fma_f32 v110, v111, v108, v108
	v_exp_f32_e32 v82, v82
	v_fma_f32 v93, -v88, v92, 1.0
	v_add_f32_e32 v64, 1.0, v64
	v_fma_f32 v99, -v94, v98, 1.0
	v_add_f32_e32 v70, 1.0, v70
	v_fma_f32 v105, -v100, v104, 1.0
	v_add_f32_e32 v76, 1.0, v76
	v_fma_f32 v111, -v106, v110, 1.0
	v_add_f32_e32 v82, 1.0, v82
	v_fma_f32 v89, v93, v90, v92
	v_rcp_f32_e32 v66, v64
	v_fma_f32 v95, v99, v96, v98
	v_rcp_f32_e32 v72, v70
	v_fma_f32 v101, v105, v102, v104
	v_rcp_f32_e32 v78, v76
	v_fma_f32 v107, v111, v108, v110
	v_rcp_f32_e32 v84, v82
	v_fma_f32 v69, -v64, v66, 1.0
	v_fma_f32 v75, -v70, v72, 1.0
	v_fma_f32 v81, -v76, v78, 1.0
	v_fma_f32 v87, -v82, v84, 1.0
	v_fmac_f32_e32 v66, v69, v66
	v_fmac_f32_e32 v72, v75, v72
	v_fmac_f32_e32 v78, v81, v78
	v_fmac_f32_e32 v84, v87, v84
	v_div_fixup_f32 v89, v89, v88, 1.0
	v_div_fixup_f32 v95, v95, v94, 1.0
	v_div_fixup_f32 v101, v101, v100, 1.0
	v_div_fixup_f32 v107, v107, v106, 1.0
	v_mul_f32_e32 v89, v52, v89
	v_mul_f32_e32 v95, v53, v95
	v_mul_f32_e32 v101, v54, v101
	v_mul_f32_e32 v107, v55, v107
	v_mul_f32_e32 v89, v36, v89
	v_mul_f32_e32 v95, v37, v95
	v_mul_f32_e32 v101, v38, v101
	v_mul_f32_e32 v107, v39, v107
	v_cvt_pk_bf16_f32 v89, v89, v89
	v_cvt_pk_bf16_f32 v95, v95, v95
	v_cvt_pk_bf16_f32 v101, v101, v101
	v_cvt_pk_bf16_f32 v107, v107, v107
	ds_write_b16 v112, v89 offset:512
	ds_write_b16 v112, v95 offset:576
	ds_write_b16 v112, v101 offset:640
	ds_write_b16 v112, v107 offset:704
	v_fma_f32 v69, -v64, v66, 1.0
	v_mul_f32_e32 v88, 0xbfb8aa3b, v60
	v_fma_f32 v75, -v70, v72, 1.0
	v_mul_f32_e32 v94, 0xbfb8aa3b, v61
	v_fma_f32 v81, -v76, v78, 1.0
	v_mul_f32_e32 v100, 0xbfb8aa3b, v62
	v_fma_f32 v87, -v82, v84, 1.0
	v_mul_f32_e32 v106, 0xbfb8aa3b, v63
	v_fma_f32 v68, v69, v66, v66
	v_exp_f32_e32 v88, v88
	v_fma_f32 v74, v75, v72, v72
	v_exp_f32_e32 v94, v94
	v_fma_f32 v80, v81, v78, v78
	v_exp_f32_e32 v100, v100
	v_fma_f32 v86, v87, v84, v84
	v_exp_f32_e32 v106, v106
	v_fma_f32 v69, -v64, v68, 1.0
	v_add_f32_e32 v88, 1.0, v88
	v_fma_f32 v75, -v70, v74, 1.0
	v_add_f32_e32 v94, 1.0, v94
	v_fma_f32 v81, -v76, v80, 1.0
	v_add_f32_e32 v100, 1.0, v100
	v_fma_f32 v87, -v82, v86, 1.0
	v_add_f32_e32 v106, 1.0, v106
	v_fma_f32 v65, v69, v66, v68
	v_rcp_f32_e32 v90, v88
	v_fma_f32 v71, v75, v72, v74
	v_rcp_f32_e32 v96, v94
	v_fma_f32 v77, v81, v78, v80
	v_rcp_f32_e32 v102, v100
	v_fma_f32 v83, v87, v84, v86
	v_rcp_f32_e32 v108, v106
	v_fma_f32 v93, -v88, v90, 1.0
	v_fma_f32 v99, -v94, v96, 1.0
	v_fma_f32 v105, -v100, v102, 1.0
	v_fma_f32 v111, -v106, v108, 1.0
	v_fmac_f32_e32 v90, v93, v90
	v_fmac_f32_e32 v96, v99, v96
	v_fmac_f32_e32 v102, v105, v102
	v_fmac_f32_e32 v108, v111, v108
	v_div_fixup_f32 v65, v65, v64, 1.0
	v_div_fixup_f32 v71, v71, v70, 1.0
	v_div_fixup_f32 v77, v77, v76, 1.0
	v_div_fixup_f32 v83, v83, v82, 1.0
	v_mul_f32_e32 v65, v56, v65
	v_mul_f32_e32 v71, v57, v71
	v_mul_f32_e32 v77, v58, v77
	v_mul_f32_e32 v83, v59, v83
	v_mul_f32_e32 v65, v40, v65
	v_mul_f32_e32 v71, v41, v71
	v_mul_f32_e32 v77, v42, v77
	v_mul_f32_e32 v83, v43, v83
	v_cvt_pk_bf16_f32 v65, v65, v65
	v_cvt_pk_bf16_f32 v71, v71, v71
	v_cvt_pk_bf16_f32 v77, v77, v77
	v_cvt_pk_bf16_f32 v83, v83, v83
	ds_write_b16 v112, v65 offset:1024
	ds_write_b16 v112, v71 offset:1088
	ds_write_b16 v112, v77 offset:1152
	ds_write_b16 v112, v83 offset:1216
	v_fma_f32 v93, -v88, v90, 1.0
	v_mul_f32_e32 v64, 0xbfb8aa3b, v16
	v_fma_f32 v99, -v94, v96, 1.0
	v_mul_f32_e32 v70, 0xbfb8aa3b, v17
	v_fma_f32 v105, -v100, v102, 1.0
	v_mul_f32_e32 v76, 0xbfb8aa3b, v18
	v_fma_f32 v111, -v106, v108, 1.0
	v_mul_f32_e32 v82, 0xbfb8aa3b, v19
	v_fma_f32 v92, v93, v90, v90
	v_exp_f32_e32 v64, v64
	v_fma_f32 v98, v99, v96, v96
	v_exp_f32_e32 v70, v70
	v_fma_f32 v104, v105, v102, v102
	v_exp_f32_e32 v76, v76
	v_fma_f32 v110, v111, v108, v108
	v_exp_f32_e32 v82, v82
	v_fma_f32 v93, -v88, v92, 1.0
	v_add_f32_e32 v64, 1.0, v64
	v_fma_f32 v99, -v94, v98, 1.0
	v_add_f32_e32 v70, 1.0, v70
	v_fma_f32 v105, -v100, v104, 1.0
	v_add_f32_e32 v76, 1.0, v76
	v_fma_f32 v111, -v106, v110, 1.0
	v_add_f32_e32 v82, 1.0, v82
	v_fma_f32 v89, v93, v90, v92
	v_rcp_f32_e32 v66, v64
	v_fma_f32 v95, v99, v96, v98
	v_rcp_f32_e32 v72, v70
	v_fma_f32 v101, v105, v102, v104
	v_rcp_f32_e32 v78, v76
	v_fma_f32 v107, v111, v108, v110
	v_rcp_f32_e32 v84, v82
	v_fma_f32 v69, -v64, v66, 1.0
	v_fma_f32 v75, -v70, v72, 1.0
	v_fma_f32 v81, -v76, v78, 1.0
	v_fma_f32 v87, -v82, v84, 1.0
	v_fmac_f32_e32 v66, v69, v66
	v_fmac_f32_e32 v72, v75, v72
	v_fmac_f32_e32 v78, v81, v78
	v_fmac_f32_e32 v84, v87, v84
	v_div_fixup_f32 v89, v89, v88, 1.0
	v_div_fixup_f32 v95, v95, v94, 1.0
	v_div_fixup_f32 v101, v101, v100, 1.0
	v_div_fixup_f32 v107, v107, v106, 1.0
	v_mul_f32_e32 v89, v60, v89
	v_mul_f32_e32 v95, v61, v95
	v_mul_f32_e32 v101, v62, v101
	v_mul_f32_e32 v107, v63, v107
	v_mul_f32_e32 v89, v44, v89
	v_mul_f32_e32 v95, v45, v95
	v_mul_f32_e32 v101, v46, v101
	v_mul_f32_e32 v107, v47, v107
	v_cvt_pk_bf16_f32 v89, v89, v89
	v_cvt_pk_bf16_f32 v95, v95, v95
	v_cvt_pk_bf16_f32 v101, v101, v101
	v_cvt_pk_bf16_f32 v107, v107, v107
	ds_write_b16 v112, v89 offset:1536
	ds_write_b16 v112, v95 offset:1600
	ds_write_b16 v112, v101 offset:1664
	ds_write_b16 v112, v107 offset:1728
	ds_read_b128 v[120:123], v113
	ds_read_b128 v[124:127], v113 offset:1024
	v_fma_f32 v69, -v64, v66, 1.0
	v_mul_f32_e32 v88, 0xbfb8aa3b, v20
	v_fma_f32 v75, -v70, v72, 1.0
	v_mul_f32_e32 v94, 0xbfb8aa3b, v21
	v_fma_f32 v81, -v76, v78, 1.0
	v_mul_f32_e32 v100, 0xbfb8aa3b, v22
	v_fma_f32 v87, -v82, v84, 1.0
	v_mul_f32_e32 v106, 0xbfb8aa3b, v23
	v_fma_f32 v68, v69, v66, v66
	v_exp_f32_e32 v88, v88
	v_fma_f32 v74, v75, v72, v72
	v_exp_f32_e32 v94, v94
	v_fma_f32 v80, v81, v78, v78
	v_exp_f32_e32 v100, v100
	v_fma_f32 v86, v87, v84, v84
	v_exp_f32_e32 v106, v106
	v_fma_f32 v69, -v64, v68, 1.0
	v_add_f32_e32 v88, 1.0, v88
	v_fma_f32 v75, -v70, v74, 1.0
	v_add_f32_e32 v94, 1.0, v94
	v_fma_f32 v81, -v76, v80, 1.0
	v_add_f32_e32 v100, 1.0, v100
	v_fma_f32 v87, -v82, v86, 1.0
	v_add_f32_e32 v106, 1.0, v106
	v_fma_f32 v65, v69, v66, v68
	v_rcp_f32_e32 v90, v88
	v_fma_f32 v71, v75, v72, v74
	v_rcp_f32_e32 v96, v94
	v_fma_f32 v77, v81, v78, v80
	v_rcp_f32_e32 v102, v100
	v_fma_f32 v83, v87, v84, v86
	v_rcp_f32_e32 v108, v106
	v_fma_f32 v93, -v88, v90, 1.0
	v_fma_f32 v99, -v94, v96, 1.0
	v_fma_f32 v105, -v100, v102, 1.0
	v_fma_f32 v111, -v106, v108, 1.0
	v_fmac_f32_e32 v90, v93, v90
	v_fmac_f32_e32 v96, v99, v96
	v_fmac_f32_e32 v102, v105, v102
	v_fmac_f32_e32 v108, v111, v108
	s_waitcnt lgkmcnt(0)
	global_store_dwordx4 v114, v[120:123], s[98:99]
	s_add_u32 s98, s98, 0x16000
	s_addc_u32 s99, s99, 0
	global_store_dwordx4 v114, v[124:127], s[98:99]
	s_add_u32 s98, s98, 0x16000
	s_addc_u32 s99, s99, 0
	v_div_fixup_f32 v65, v65, v64, 1.0
	v_div_fixup_f32 v71, v71, v70, 1.0
	v_div_fixup_f32 v77, v77, v76, 1.0
	v_div_fixup_f32 v83, v83, v82, 1.0
	v_mul_f32_e32 v65, v16, v65
	v_mul_f32_e32 v71, v17, v71
	v_mul_f32_e32 v77, v18, v77
	v_mul_f32_e32 v83, v19, v83
	v_mul_f32_e32 v65, v0, v65
	v_mul_f32_e32 v71, v1, v71
	v_mul_f32_e32 v77, v2, v77
	v_mul_f32_e32 v83, v3, v83
	v_cvt_pk_bf16_f32 v65, v65, v65
	v_cvt_pk_bf16_f32 v71, v71, v71
	v_cvt_pk_bf16_f32 v77, v77, v77
	v_cvt_pk_bf16_f32 v83, v83, v83
	ds_write_b16 v112, v65
	ds_write_b16 v112, v71 offset:64
	ds_write_b16 v112, v77 offset:128
	ds_write_b16 v112, v83 offset:192
	v_fma_f32 v93, -v88, v90, 1.0
	v_mul_f32_e32 v64, 0xbfb8aa3b, v24
	v_fma_f32 v99, -v94, v96, 1.0
	v_mul_f32_e32 v70, 0xbfb8aa3b, v25
	v_fma_f32 v105, -v100, v102, 1.0
	v_mul_f32_e32 v76, 0xbfb8aa3b, v26
	v_fma_f32 v111, -v106, v108, 1.0
	v_mul_f32_e32 v82, 0xbfb8aa3b, v27
	v_fma_f32 v92, v93, v90, v90
	v_exp_f32_e32 v64, v64
	v_fma_f32 v98, v99, v96, v96
	v_exp_f32_e32 v70, v70
	v_fma_f32 v104, v105, v102, v102
	v_exp_f32_e32 v76, v76
	v_fma_f32 v110, v111, v108, v108
	v_exp_f32_e32 v82, v82
	v_fma_f32 v93, -v88, v92, 1.0
	v_add_f32_e32 v64, 1.0, v64
	v_fma_f32 v99, -v94, v98, 1.0
	v_add_f32_e32 v70, 1.0, v70
	v_fma_f32 v105, -v100, v104, 1.0
	v_add_f32_e32 v76, 1.0, v76
	v_fma_f32 v111, -v106, v110, 1.0
	v_add_f32_e32 v82, 1.0, v82
	v_fma_f32 v89, v93, v90, v92
	v_rcp_f32_e32 v66, v64
	v_fma_f32 v95, v99, v96, v98
	v_rcp_f32_e32 v72, v70
	v_fma_f32 v101, v105, v102, v104
	v_rcp_f32_e32 v78, v76
	v_fma_f32 v107, v111, v108, v110
	v_rcp_f32_e32 v84, v82
	v_fma_f32 v69, -v64, v66, 1.0
	v_fma_f32 v75, -v70, v72, 1.0
	v_fma_f32 v81, -v76, v78, 1.0
	v_fma_f32 v87, -v82, v84, 1.0
	v_fmac_f32_e32 v66, v69, v66
	v_fmac_f32_e32 v72, v75, v72
	v_fmac_f32_e32 v78, v81, v78
	v_fmac_f32_e32 v84, v87, v84
	v_div_fixup_f32 v89, v89, v88, 1.0
	v_div_fixup_f32 v95, v95, v94, 1.0
	v_div_fixup_f32 v101, v101, v100, 1.0
	v_div_fixup_f32 v107, v107, v106, 1.0
	v_mul_f32_e32 v89, v20, v89
	v_mul_f32_e32 v95, v21, v95
	v_mul_f32_e32 v101, v22, v101
	v_mul_f32_e32 v107, v23, v107
	v_mul_f32_e32 v89, v4, v89
	v_mul_f32_e32 v95, v5, v95
	v_mul_f32_e32 v101, v6, v101
	v_mul_f32_e32 v107, v7, v107
	v_cvt_pk_bf16_f32 v89, v89, v89
	v_cvt_pk_bf16_f32 v95, v95, v95
	v_cvt_pk_bf16_f32 v101, v101, v101
	v_cvt_pk_bf16_f32 v107, v107, v107
	ds_write_b16 v112, v89 offset:512
	ds_write_b16 v112, v95 offset:576
	ds_write_b16 v112, v101 offset:640
	ds_write_b16 v112, v107 offset:704
	v_fma_f32 v69, -v64, v66, 1.0
	v_mul_f32_e32 v88, 0xbfb8aa3b, v28
	v_fma_f32 v75, -v70, v72, 1.0
	v_mul_f32_e32 v94, 0xbfb8aa3b, v29
	v_fma_f32 v81, -v76, v78, 1.0
	v_mul_f32_e32 v100, 0xbfb8aa3b, v30
	v_fma_f32 v87, -v82, v84, 1.0
	v_mul_f32_e32 v106, 0xbfb8aa3b, v31
	v_fma_f32 v68, v69, v66, v66
	v_exp_f32_e32 v88, v88
	v_fma_f32 v74, v75, v72, v72
	v_exp_f32_e32 v94, v94
	v_fma_f32 v80, v81, v78, v78
	v_exp_f32_e32 v100, v100
	v_fma_f32 v86, v87, v84, v84
	v_exp_f32_e32 v106, v106
	v_fma_f32 v69, -v64, v68, 1.0
	v_add_f32_e32 v88, 1.0, v88
	v_fma_f32 v75, -v70, v74, 1.0
	v_add_f32_e32 v94, 1.0, v94
	v_fma_f32 v81, -v76, v80, 1.0
	v_add_f32_e32 v100, 1.0, v100
	v_fma_f32 v87, -v82, v86, 1.0
	v_add_f32_e32 v106, 1.0, v106
	v_fma_f32 v65, v69, v66, v68
	v_rcp_f32_e32 v90, v88
	v_fma_f32 v71, v75, v72, v74
	v_rcp_f32_e32 v96, v94
	v_fma_f32 v77, v81, v78, v80
	v_rcp_f32_e32 v102, v100
	v_fma_f32 v83, v87, v84, v86
	v_rcp_f32_e32 v108, v106
	v_fma_f32 v93, -v88, v90, 1.0
	v_fma_f32 v99, -v94, v96, 1.0
	v_fma_f32 v105, -v100, v102, 1.0
	v_fma_f32 v111, -v106, v108, 1.0
	v_fmac_f32_e32 v90, v93, v90
	v_fmac_f32_e32 v96, v99, v96
	v_fmac_f32_e32 v102, v105, v102
	v_fmac_f32_e32 v108, v111, v108
	v_div_fixup_f32 v65, v65, v64, 1.0
	v_div_fixup_f32 v71, v71, v70, 1.0
	v_div_fixup_f32 v77, v77, v76, 1.0
	v_div_fixup_f32 v83, v83, v82, 1.0
	v_mul_f32_e32 v65, v24, v65
	v_mul_f32_e32 v71, v25, v71
	v_mul_f32_e32 v77, v26, v77
	v_mul_f32_e32 v83, v27, v83
	v_mul_f32_e32 v65, v8, v65
	v_mul_f32_e32 v71, v9, v71
	v_mul_f32_e32 v77, v10, v77
	v_mul_f32_e32 v83, v11, v83
	v_cvt_pk_bf16_f32 v65, v65, v65
	v_cvt_pk_bf16_f32 v71, v71, v71
	v_cvt_pk_bf16_f32 v77, v77, v77
	v_cvt_pk_bf16_f32 v83, v83, v83
	ds_write_b16 v112, v65 offset:1024
	ds_write_b16 v112, v71 offset:1088
	ds_write_b16 v112, v77 offset:1152
	ds_write_b16 v112, v83 offset:1216
	v_fma_f32 v93, -v88, v90, 1.0
	v_fma_f32 v99, -v94, v96, 1.0
	v_fma_f32 v105, -v100, v102, 1.0
	v_fma_f32 v111, -v106, v108, 1.0
	v_fma_f32 v92, v93, v90, v90
	v_fma_f32 v98, v99, v96, v96
	v_fma_f32 v104, v105, v102, v102
	v_fma_f32 v110, v111, v108, v108
	v_fma_f32 v93, -v88, v92, 1.0
	v_fma_f32 v99, -v94, v98, 1.0
	v_fma_f32 v105, -v100, v104, 1.0
	v_fma_f32 v111, -v106, v110, 1.0
	v_fma_f32 v89, v93, v90, v92
	v_fma_f32 v95, v99, v96, v98
	v_fma_f32 v101, v105, v102, v104
	v_fma_f32 v107, v111, v108, v110
	v_div_fixup_f32 v89, v89, v88, 1.0
	v_div_fixup_f32 v95, v95, v94, 1.0
	v_div_fixup_f32 v101, v101, v100, 1.0
	v_div_fixup_f32 v107, v107, v106, 1.0
	v_mul_f32_e32 v89, v28, v89
	v_mul_f32_e32 v95, v29, v95
	v_mul_f32_e32 v101, v30, v101
	v_mul_f32_e32 v107, v31, v107
	v_mul_f32_e32 v89, v12, v89
	v_mul_f32_e32 v95, v13, v95
	v_mul_f32_e32 v101, v14, v101
	v_mul_f32_e32 v107, v15, v107
	v_cvt_pk_bf16_f32 v89, v89, v89
	v_cvt_pk_bf16_f32 v95, v95, v95
	v_cvt_pk_bf16_f32 v101, v101, v101
	v_cvt_pk_bf16_f32 v107, v107, v107
	ds_write_b16 v112, v89 offset:1536
	ds_write_b16 v112, v95 offset:1600
	ds_write_b16 v112, v101 offset:1664
	ds_write_b16 v112, v107 offset:1728
	ds_read_b128 v[120:123], v113
	ds_read_b128 v[124:127], v113 offset:1024
	s_waitcnt lgkmcnt(0)
	global_store_dwordx4 v114, v[120:123], s[98:99]
	s_add_u32 s98, s98, 0x16000
	s_addc_u32 s99, s99, 0
	global_store_dwordx4 v114, v[124:127], s[98:99]
	s_add_u32 s98, s98, 0x16000
	s_addc_u32 s99, s99, 0
	s_add_i32 s57, s57, s92
	s_cmpk_gt_i32 s57, 0x107f
	s_cbranch_scc1 .LBB0_1043

.LBB0_2283:
	v_lshl_or_b32 v115, v183, 3, v191
	v_lshrrev_b32_e32 v116, 6, v115
	v_and_b32_e32 v117, 63, v115
	v_lshlrev_b32_e32 v113, 11, v116
	v_add_u32_e32 v113, 0x10000, v113
	v_readfirstlane_b32 s100, v116
	v_and_b32_e32 v112, 31, v117
	v_lshl_add_u32 v112, v112, 1, v113
	v_lshrrev_b32_e32 v116, 5, v117
	v_lshl_add_u32 v112, v116, 8, v112
	v_lshl_add_u32 v113, v117, 4, v113
	v_lshrrev_b32_e32 v116, 2, v117
	v_mul_u32_u24_e32 v116, 0x1600, v116
	v_and_b32_e32 v114, 3, v117
	v_lshl_add_u32 v114, v114, 4, v116
	s_lshr_b32 s101, s100, 1
	s_lshl_b32 s101, s101, 6
	s_add_u32 s101, s101, s48
	s_mul_i32 s101, s101, 0x1600
	s_and_b32 s100, s100, 1
	s_lshl_b32 s100, s100, 6
	s_add_u32 s100, s100, s49
	s_add_u32 s101, s101, s100
	s_add_u32 s98, s90, 0x3971900
	s_addc_u32 s99, s91, 0
	s_add_u32 s98, s98, s101
	s_addc_u32 s99, s99, 0
	v_mul_f32_e32 v64, 0xbfb8aa3b, v48
	v_mul_f32_e32 v70, 0xbfb8aa3b, v49
	v_mul_f32_e32 v76, 0xbfb8aa3b, v50
	v_mul_f32_e32 v82, 0xbfb8aa3b, v51
	v_exp_f32_e32 v64, v64
	v_exp_f32_e32 v70, v70
	v_exp_f32_e32 v76, v76
	v_exp_f32_e32 v82, v82
	v_add_f32_e32 v64, 1.0, v64
	v_add_f32_e32 v70, 1.0, v70
	v_add_f32_e32 v76, 1.0, v76
	v_add_f32_e32 v82, 1.0, v82
	v_rcp_f32_e32 v66, v64
	v_rcp_f32_e32 v72, v70
	v_rcp_f32_e32 v78, v76
	v_rcp_f32_e32 v84, v82
	v_fma_f32 v69, -v64, v66, 1.0
	v_fma_f32 v75, -v70, v72, 1.0
	v_fma_f32 v81, -v76, v78, 1.0
	v_fma_f32 v87, -v82, v84, 1.0
	v_fmac_f32_e32 v66, v69, v66
	v_fmac_f32_e32 v72, v75, v72
	v_fmac_f32_e32 v78, v81, v78
	v_fmac_f32_e32 v84, v87, v84
	v_fma_f32 v69, -v64, v66, 1.0
	v_mul_f32_e32 v88, 0xbfb8aa3b, v52
	v_fma_f32 v75, -v70, v72, 1.0
	v_mul_f32_e32 v94, 0xbfb8aa3b, v53
	v_fma_f32 v81, -v76, v78, 1.0
	v_mul_f32_e32 v100, 0xbfb8aa3b, v54
	v_fma_f32 v87, -v82, v84, 1.0
	v_mul_f32_e32 v106, 0xbfb8aa3b, v55
	v_fma_f32 v68, v69, v66, v66
	v_exp_f32_e32 v88, v88
	v_fma_f32 v74, v75, v72, v72
	v_exp_f32_e32 v94, v94
	v_fma_f32 v80, v81, v78, v78
	v_exp_f32_e32 v100, v100
	v_fma_f32 v86, v87, v84, v84
	v_exp_f32_e32 v106, v106
	v_fma_f32 v69, -v64, v68, 1.0
	v_add_f32_e32 v88, 1.0, v88
	v_fma_f32 v75, -v70, v74, 1.0
	v_add_f32_e32 v94, 1.0, v94
	v_fma_f32 v81, -v76, v80, 1.0
	v_add_f32_e32 v100, 1.0, v100
	v_fma_f32 v87, -v82, v86, 1.0
	v_add_f32_e32 v106, 1.0, v106
	v_fma_f32 v65, v69, v66, v68
	v_rcp_f32_e32 v90, v88
	v_fma_f32 v71, v75, v72, v74
	v_rcp_f32_e32 v96, v94
	v_fma_f32 v77, v81, v78, v80
	v_rcp_f32_e32 v102, v100
	v_fma_f32 v83, v87, v84, v86
	v_rcp_f32_e32 v108, v106
	v_fma_f32 v93, -v88, v90, 1.0
	v_fma_f32 v99, -v94, v96, 1.0
	v_fma_f32 v105, -v100, v102, 1.0
	v_fma_f32 v111, -v106, v108, 1.0
	v_fmac_f32_e32 v90, v93, v90
	v_fmac_f32_e32 v96, v99, v96
	v_fmac_f32_e32 v102, v105, v102
	v_fmac_f32_e32 v108, v111, v108
	v_div_fixup_f32 v65, v65, v64, 1.0
	v_div_fixup_f32 v71, v71, v70, 1.0
	v_div_fixup_f32 v77, v77, v76, 1.0
	v_div_fixup_f32 v83, v83, v82, 1.0
	v_mul_f32_e32 v65, v48, v65
	v_mul_f32_e32 v71, v49, v71
	v_mul_f32_e32 v77, v50, v77
	v_mul_f32_e32 v83, v51, v83
	v_mul_f32_e32 v65, v32, v65
	v_mul_f32_e32 v71, v33, v71
	v_mul_f32_e32 v77, v34, v77
	v_mul_f32_e32 v83, v35, v83
	v_cvt_pk_bf16_f32 v65, v65, v65
	v_cvt_pk_bf16_f32 v71, v71, v71
	v_cvt_pk_bf16_f32 v77, v77, v77
	v_cvt_pk_bf16_f32 v83, v83, v83
	ds_write_b16 v112, v65
	ds_write_b16 v112, v71 offset:64
	ds_write_b16 v112, v77 offset:128
	ds_write_b16 v112, v83 offset:192
	v_fma_f32 v93, -v88, v90, 1.0
	v_mul_f32_e32 v64, 0xbfb8aa3b, v56
	v_fma_f32 v99, -v94, v96, 1.0
	v_mul_f32_e32 v70, 0xbfb8aa3b, v57
	v_fma_f32 v105, -v100, v102, 1.0
	v_mul_f32_e32 v76, 0xbfb8aa3b, v58
	v_fma_f32 v111, -v106, v108, 1.0
	v_mul_f32_e32 v82, 0xbfb8aa3b, v59
	v_fma_f32 v92, v93, v90, v90
	v_exp_f32_e32 v64, v64
	v_fma_f32 v98, v99, v96, v96
	v_exp_f32_e32 v70, v70
	v_fma_f32 v104, v105, v102, v102
	v_exp_f32_e32 v76, v76
	v_fma_f32 v110, v111, v108, v108
	v_exp_f32_e32 v82, v82
	v_fma_f32 v93, -v88, v92, 1.0
	v_add_f32_e32 v64, 1.0, v64
	v_fma_f32 v99, -v94, v98, 1.0
	v_add_f32_e32 v70, 1.0, v70
	v_fma_f32 v105, -v100, v104, 1.0
	v_add_f32_e32 v76, 1.0, v76
	v_fma_f32 v111, -v106, v110, 1.0
	v_add_f32_e32 v82, 1.0, v82
	v_fma_f32 v89, v93, v90, v92
	v_rcp_f32_e32 v66, v64
	v_fma_f32 v95, v99, v96, v98
	v_rcp_f32_e32 v72, v70
	v_fma_f32 v101, v105, v102, v104
	v_rcp_f32_e32 v78, v76
	v_fma_f32 v107, v111, v108, v110
	v_rcp_f32_e32 v84, v82
	v_fma_f32 v69, -v64, v66, 1.0
	v_fma_f32 v75, -v70, v72, 1.0
	v_fma_f32 v81, -v76, v78, 1.0
	v_fma_f32 v87, -v82, v84, 1.0
	v_fmac_f32_e32 v66, v69, v66
	v_fmac_f32_e32 v72, v75, v72
	v_fmac_f32_e32 v78, v81, v78
	v_fmac_f32_e32 v84, v87, v84
	v_div_fixup_f32 v89, v89, v88, 1.0
	v_div_fixup_f32 v95, v95, v94, 1.0
	v_div_fixup_f32 v101, v101, v100, 1.0
	v_div_fixup_f32 v107, v107, v106, 1.0
	v_mul_f32_e32 v89, v52, v89
	v_mul_f32_e32 v95, v53, v95
	v_mul_f32_e32 v101, v54, v101
	v_mul_f32_e32 v107, v55, v107
	v_mul_f32_e32 v89, v36, v89
	v_mul_f32_e32 v95, v37, v95
	v_mul_f32_e32 v101, v38, v101
	v_mul_f32_e32 v107, v39, v107
	v_cvt_pk_bf16_f32 v89, v89, v89
	v_cvt_pk_bf16_f32 v95, v95, v95
	v_cvt_pk_bf16_f32 v101, v101, v101
	v_cvt_pk_bf16_f32 v107, v107, v107
	ds_write_b16 v112, v89 offset:512
	ds_write_b16 v112, v95 offset:576
	ds_write_b16 v112, v101 offset:640
	ds_write_b16 v112, v107 offset:704
	v_fma_f32 v69, -v64, v66, 1.0
	v_mul_f32_e32 v88, 0xbfb8aa3b, v60
	v_fma_f32 v75, -v70, v72, 1.0
	v_mul_f32_e32 v94, 0xbfb8aa3b, v61
	v_fma_f32 v81, -v76, v78, 1.0
	v_mul_f32_e32 v100, 0xbfb8aa3b, v62
	v_fma_f32 v87, -v82, v84, 1.0
	v_mul_f32_e32 v106, 0xbfb8aa3b, v63
	v_fma_f32 v68, v69, v66, v66
	v_exp_f32_e32 v88, v88
	v_fma_f32 v74, v75, v72, v72
	v_exp_f32_e32 v94, v94
	v_fma_f32 v80, v81, v78, v78
	v_exp_f32_e32 v100, v100
	v_fma_f32 v86, v87, v84, v84
	v_exp_f32_e32 v106, v106
	v_fma_f32 v69, -v64, v68, 1.0
	v_add_f32_e32 v88, 1.0, v88
	v_fma_f32 v75, -v70, v74, 1.0
	v_add_f32_e32 v94, 1.0, v94
	v_fma_f32 v81, -v76, v80, 1.0
	v_add_f32_e32 v100, 1.0, v100
	v_fma_f32 v87, -v82, v86, 1.0
	v_add_f32_e32 v106, 1.0, v106
	v_fma_f32 v65, v69, v66, v68
	v_rcp_f32_e32 v90, v88
	v_fma_f32 v71, v75, v72, v74
	v_rcp_f32_e32 v96, v94
	v_fma_f32 v77, v81, v78, v80
	v_rcp_f32_e32 v102, v100
	v_fma_f32 v83, v87, v84, v86
	v_rcp_f32_e32 v108, v106
	v_fma_f32 v93, -v88, v90, 1.0
	v_fma_f32 v99, -v94, v96, 1.0
	v_fma_f32 v105, -v100, v102, 1.0
	v_fma_f32 v111, -v106, v108, 1.0
	v_fmac_f32_e32 v90, v93, v90
	v_fmac_f32_e32 v96, v99, v96
	v_fmac_f32_e32 v102, v105, v102
	v_fmac_f32_e32 v108, v111, v108
	v_div_fixup_f32 v65, v65, v64, 1.0
	v_div_fixup_f32 v71, v71, v70, 1.0
	v_div_fixup_f32 v77, v77, v76, 1.0
	v_div_fixup_f32 v83, v83, v82, 1.0
	v_mul_f32_e32 v65, v56, v65
	v_mul_f32_e32 v71, v57, v71
	v_mul_f32_e32 v77, v58, v77
	v_mul_f32_e32 v83, v59, v83
	v_mul_f32_e32 v65, v40, v65
	v_mul_f32_e32 v71, v41, v71
	v_mul_f32_e32 v77, v42, v77
	v_mul_f32_e32 v83, v43, v83
	v_cvt_pk_bf16_f32 v65, v65, v65
	v_cvt_pk_bf16_f32 v71, v71, v71
	v_cvt_pk_bf16_f32 v77, v77, v77
	v_cvt_pk_bf16_f32 v83, v83, v83
	ds_write_b16 v112, v65 offset:1024
	ds_write_b16 v112, v71 offset:1088
	ds_write_b16 v112, v77 offset:1152
	ds_write_b16 v112, v83 offset:1216
	v_fma_f32 v93, -v88, v90, 1.0
	v_mul_f32_e32 v64, 0xbfb8aa3b, v16
	v_fma_f32 v99, -v94, v96, 1.0
	v_mul_f32_e32 v70, 0xbfb8aa3b, v17
	v_fma_f32 v105, -v100, v102, 1.0
	v_mul_f32_e32 v76, 0xbfb8aa3b, v18
	v_fma_f32 v111, -v106, v108, 1.0
	v_mul_f32_e32 v82, 0xbfb8aa3b, v19
	v_fma_f32 v92, v93, v90, v90
	v_exp_f32_e32 v64, v64
	v_fma_f32 v98, v99, v96, v96
	v_exp_f32_e32 v70, v70
	v_fma_f32 v104, v105, v102, v102
	v_exp_f32_e32 v76, v76
	v_fma_f32 v110, v111, v108, v108
	v_exp_f32_e32 v82, v82
	v_fma_f32 v93, -v88, v92, 1.0
	v_add_f32_e32 v64, 1.0, v64
	v_fma_f32 v99, -v94, v98, 1.0
	v_add_f32_e32 v70, 1.0, v70
	v_fma_f32 v105, -v100, v104, 1.0
	v_add_f32_e32 v76, 1.0, v76
	v_fma_f32 v111, -v106, v110, 1.0
	v_add_f32_e32 v82, 1.0, v82
	v_fma_f32 v89, v93, v90, v92
	v_rcp_f32_e32 v66, v64
	v_fma_f32 v95, v99, v96, v98
	v_rcp_f32_e32 v72, v70
	v_fma_f32 v101, v105, v102, v104
	v_rcp_f32_e32 v78, v76
	v_fma_f32 v107, v111, v108, v110
	v_rcp_f32_e32 v84, v82
	v_fma_f32 v69, -v64, v66, 1.0
	v_fma_f32 v75, -v70, v72, 1.0
	v_fma_f32 v81, -v76, v78, 1.0
	v_fma_f32 v87, -v82, v84, 1.0
	v_fmac_f32_e32 v66, v69, v66
	v_fmac_f32_e32 v72, v75, v72
	v_fmac_f32_e32 v78, v81, v78
	v_fmac_f32_e32 v84, v87, v84
	v_div_fixup_f32 v89, v89, v88, 1.0
	v_div_fixup_f32 v95, v95, v94, 1.0
	v_div_fixup_f32 v101, v101, v100, 1.0
	v_div_fixup_f32 v107, v107, v106, 1.0
	v_mul_f32_e32 v89, v60, v89
	v_mul_f32_e32 v95, v61, v95
	v_mul_f32_e32 v101, v62, v101
	v_mul_f32_e32 v107, v63, v107
	v_mul_f32_e32 v89, v44, v89
	v_mul_f32_e32 v95, v45, v95
	v_mul_f32_e32 v101, v46, v101
	v_mul_f32_e32 v107, v47, v107
	v_cvt_pk_bf16_f32 v89, v89, v89
	v_cvt_pk_bf16_f32 v95, v95, v95
	v_cvt_pk_bf16_f32 v101, v101, v101
	v_cvt_pk_bf16_f32 v107, v107, v107
	ds_write_b16 v112, v89 offset:1536
	ds_write_b16 v112, v95 offset:1600
	ds_write_b16 v112, v101 offset:1664
	ds_write_b16 v112, v107 offset:1728
	ds_read_b128 v[120:123], v113
	ds_read_b128 v[124:127], v113 offset:1024
	v_fma_f32 v69, -v64, v66, 1.0
	v_mul_f32_e32 v88, 0xbfb8aa3b, v20
	v_fma_f32 v75, -v70, v72, 1.0
	v_mul_f32_e32 v94, 0xbfb8aa3b, v21
	v_fma_f32 v81, -v76, v78, 1.0
	v_mul_f32_e32 v100, 0xbfb8aa3b, v22
	v_fma_f32 v87, -v82, v84, 1.0
	v_mul_f32_e32 v106, 0xbfb8aa3b, v23
	v_fma_f32 v68, v69, v66, v66
	v_exp_f32_e32 v88, v88
	v_fma_f32 v74, v75, v72, v72
	v_exp_f32_e32 v94, v94
	v_fma_f32 v80, v81, v78, v78
	v_exp_f32_e32 v100, v100
	v_fma_f32 v86, v87, v84, v84
	v_exp_f32_e32 v106, v106
	v_fma_f32 v69, -v64, v68, 1.0
	v_add_f32_e32 v88, 1.0, v88
	v_fma_f32 v75, -v70, v74, 1.0
	v_add_f32_e32 v94, 1.0, v94
	v_fma_f32 v81, -v76, v80, 1.0
	v_add_f32_e32 v100, 1.0, v100
	v_fma_f32 v87, -v82, v86, 1.0
	v_add_f32_e32 v106, 1.0, v106
	v_fma_f32 v65, v69, v66, v68
	v_rcp_f32_e32 v90, v88
	v_fma_f32 v71, v75, v72, v74
	v_rcp_f32_e32 v96, v94
	v_fma_f32 v77, v81, v78, v80
	v_rcp_f32_e32 v102, v100
	v_fma_f32 v83, v87, v84, v86
	v_rcp_f32_e32 v108, v106
	v_fma_f32 v93, -v88, v90, 1.0
	v_fma_f32 v99, -v94, v96, 1.0
	v_fma_f32 v105, -v100, v102, 1.0
	v_fma_f32 v111, -v106, v108, 1.0
	v_fmac_f32_e32 v90, v93, v90
	v_fmac_f32_e32 v96, v99, v96
	v_fmac_f32_e32 v102, v105, v102
	v_fmac_f32_e32 v108, v111, v108
	s_waitcnt lgkmcnt(0)
	global_store_dwordx4 v114, v[120:123], s[98:99]
	s_add_u32 s98, s98, 0x16000
	s_addc_u32 s99, s99, 0
	global_store_dwordx4 v114, v[124:127], s[98:99]
	s_add_u32 s98, s98, 0x16000
	s_addc_u32 s99, s99, 0
	v_div_fixup_f32 v65, v65, v64, 1.0
	v_div_fixup_f32 v71, v71, v70, 1.0
	v_div_fixup_f32 v77, v77, v76, 1.0
	v_div_fixup_f32 v83, v83, v82, 1.0
	v_mul_f32_e32 v65, v16, v65
	v_mul_f32_e32 v71, v17, v71
	v_mul_f32_e32 v77, v18, v77
	v_mul_f32_e32 v83, v19, v83
	v_mul_f32_e32 v65, v0, v65
	v_mul_f32_e32 v71, v1, v71
	v_mul_f32_e32 v77, v2, v77
	v_mul_f32_e32 v83, v3, v83
	v_cvt_pk_bf16_f32 v65, v65, v65
	v_cvt_pk_bf16_f32 v71, v71, v71
	v_cvt_pk_bf16_f32 v77, v77, v77
	v_cvt_pk_bf16_f32 v83, v83, v83
	ds_write_b16 v112, v65
	ds_write_b16 v112, v71 offset:64
	ds_write_b16 v112, v77 offset:128
	ds_write_b16 v112, v83 offset:192
	v_fma_f32 v93, -v88, v90, 1.0
	v_mul_f32_e32 v64, 0xbfb8aa3b, v24
	v_fma_f32 v99, -v94, v96, 1.0
	v_mul_f32_e32 v70, 0xbfb8aa3b, v25
	v_fma_f32 v105, -v100, v102, 1.0
	v_mul_f32_e32 v76, 0xbfb8aa3b, v26
	v_fma_f32 v111, -v106, v108, 1.0
	v_mul_f32_e32 v82, 0xbfb8aa3b, v27
	v_fma_f32 v92, v93, v90, v90
	v_exp_f32_e32 v64, v64
	v_fma_f32 v98, v99, v96, v96
	v_exp_f32_e32 v70, v70
	v_fma_f32 v104, v105, v102, v102
	v_exp_f32_e32 v76, v76
	v_fma_f32 v110, v111, v108, v108
	v_exp_f32_e32 v82, v82
	v_fma_f32 v93, -v88, v92, 1.0
	v_add_f32_e32 v64, 1.0, v64
	v_fma_f32 v99, -v94, v98, 1.0
	v_add_f32_e32 v70, 1.0, v70
	v_fma_f32 v105, -v100, v104, 1.0
	v_add_f32_e32 v76, 1.0, v76
	v_fma_f32 v111, -v106, v110, 1.0
	v_add_f32_e32 v82, 1.0, v82
	v_fma_f32 v89, v93, v90, v92
	v_rcp_f32_e32 v66, v64
	v_fma_f32 v95, v99, v96, v98
	v_rcp_f32_e32 v72, v70
	v_fma_f32 v101, v105, v102, v104
	v_rcp_f32_e32 v78, v76
	v_fma_f32 v107, v111, v108, v110
	v_rcp_f32_e32 v84, v82
	v_fma_f32 v69, -v64, v66, 1.0
	v_fma_f32 v75, -v70, v72, 1.0
	v_fma_f32 v81, -v76, v78, 1.0
	v_fma_f32 v87, -v82, v84, 1.0
	v_fmac_f32_e32 v66, v69, v66
	v_fmac_f32_e32 v72, v75, v72
	v_fmac_f32_e32 v78, v81, v78
	v_fmac_f32_e32 v84, v87, v84
	v_div_fixup_f32 v89, v89, v88, 1.0
	v_div_fixup_f32 v95, v95, v94, 1.0
	v_div_fixup_f32 v101, v101, v100, 1.0
	v_div_fixup_f32 v107, v107, v106, 1.0
	v_mul_f32_e32 v89, v20, v89
	v_mul_f32_e32 v95, v21, v95
	v_mul_f32_e32 v101, v22, v101
	v_mul_f32_e32 v107, v23, v107
	v_mul_f32_e32 v89, v4, v89
	v_mul_f32_e32 v95, v5, v95
	v_mul_f32_e32 v101, v6, v101
	v_mul_f32_e32 v107, v7, v107
	v_cvt_pk_bf16_f32 v89, v89, v89
	v_cvt_pk_bf16_f32 v95, v95, v95
	v_cvt_pk_bf16_f32 v101, v101, v101
	v_cvt_pk_bf16_f32 v107, v107, v107
	ds_write_b16 v112, v89 offset:512
	ds_write_b16 v112, v95 offset:576
	ds_write_b16 v112, v101 offset:640
	ds_write_b16 v112, v107 offset:704
	v_fma_f32 v69, -v64, v66, 1.0
	v_mul_f32_e32 v88, 0xbfb8aa3b, v28
	v_fma_f32 v75, -v70, v72, 1.0
	v_mul_f32_e32 v94, 0xbfb8aa3b, v29
	v_fma_f32 v81, -v76, v78, 1.0
	v_mul_f32_e32 v100, 0xbfb8aa3b, v30
	v_fma_f32 v87, -v82, v84, 1.0
	v_mul_f32_e32 v106, 0xbfb8aa3b, v31
	v_fma_f32 v68, v69, v66, v66
	v_exp_f32_e32 v88, v88
	v_fma_f32 v74, v75, v72, v72
	v_exp_f32_e32 v94, v94
	v_fma_f32 v80, v81, v78, v78
	v_exp_f32_e32 v100, v100
	v_fma_f32 v86, v87, v84, v84
	v_exp_f32_e32 v106, v106
	v_fma_f32 v69, -v64, v68, 1.0
	v_add_f32_e32 v88, 1.0, v88
	v_fma_f32 v75, -v70, v74, 1.0
	v_add_f32_e32 v94, 1.0, v94
	v_fma_f32 v81, -v76, v80, 1.0
	v_add_f32_e32 v100, 1.0, v100
	v_fma_f32 v87, -v82, v86, 1.0
	v_add_f32_e32 v106, 1.0, v106
	v_fma_f32 v65, v69, v66, v68
	v_rcp_f32_e32 v90, v88
	v_fma_f32 v71, v75, v72, v74
	v_rcp_f32_e32 v96, v94
	v_fma_f32 v77, v81, v78, v80
	v_rcp_f32_e32 v102, v100
	v_fma_f32 v83, v87, v84, v86
	v_rcp_f32_e32 v108, v106
	v_fma_f32 v93, -v88, v90, 1.0
	v_fma_f32 v99, -v94, v96, 1.0
	v_fma_f32 v105, -v100, v102, 1.0
	v_fma_f32 v111, -v106, v108, 1.0
	v_fmac_f32_e32 v90, v93, v90
	v_fmac_f32_e32 v96, v99, v96
	v_fmac_f32_e32 v102, v105, v102
	v_fmac_f32_e32 v108, v111, v108
	v_div_fixup_f32 v65, v65, v64, 1.0
	v_div_fixup_f32 v71, v71, v70, 1.0
	v_div_fixup_f32 v77, v77, v76, 1.0
	v_div_fixup_f32 v83, v83, v82, 1.0
	v_mul_f32_e32 v65, v24, v65
	v_mul_f32_e32 v71, v25, v71
	v_mul_f32_e32 v77, v26, v77
	v_mul_f32_e32 v83, v27, v83
	v_mul_f32_e32 v65, v8, v65
	v_mul_f32_e32 v71, v9, v71
	v_mul_f32_e32 v77, v10, v77
	v_mul_f32_e32 v83, v11, v83
	v_cvt_pk_bf16_f32 v65, v65, v65
	v_cvt_pk_bf16_f32 v71, v71, v71
	v_cvt_pk_bf16_f32 v77, v77, v77
	v_cvt_pk_bf16_f32 v83, v83, v83
	ds_write_b16 v112, v65 offset:1024
	ds_write_b16 v112, v71 offset:1088
	ds_write_b16 v112, v77 offset:1152
	ds_write_b16 v112, v83 offset:1216
	v_fma_f32 v93, -v88, v90, 1.0
	v_fma_f32 v99, -v94, v96, 1.0
	v_fma_f32 v105, -v100, v102, 1.0
	v_fma_f32 v111, -v106, v108, 1.0
	v_fma_f32 v92, v93, v90, v90
	v_fma_f32 v98, v99, v96, v96
	v_fma_f32 v104, v105, v102, v102
	v_fma_f32 v110, v111, v108, v108
	v_fma_f32 v93, -v88, v92, 1.0
	v_fma_f32 v99, -v94, v98, 1.0
	v_fma_f32 v105, -v100, v104, 1.0
	v_fma_f32 v111, -v106, v110, 1.0
	v_fma_f32 v89, v93, v90, v92
	v_fma_f32 v95, v99, v96, v98
	v_fma_f32 v101, v105, v102, v104
	v_fma_f32 v107, v111, v108, v110
	v_div_fixup_f32 v89, v89, v88, 1.0
	v_div_fixup_f32 v95, v95, v94, 1.0
	v_div_fixup_f32 v101, v101, v100, 1.0
	v_div_fixup_f32 v107, v107, v106, 1.0
	v_mul_f32_e32 v89, v28, v89
	v_mul_f32_e32 v95, v29, v95
	v_mul_f32_e32 v101, v30, v101
	v_mul_f32_e32 v107, v31, v107
	v_mul_f32_e32 v89, v12, v89
	v_mul_f32_e32 v95, v13, v95
	v_mul_f32_e32 v101, v14, v101
	v_mul_f32_e32 v107, v15, v107
	v_cvt_pk_bf16_f32 v89, v89, v89
	v_cvt_pk_bf16_f32 v95, v95, v95
	v_cvt_pk_bf16_f32 v101, v101, v101
	v_cvt_pk_bf16_f32 v107, v107, v107
	ds_write_b16 v112, v89 offset:1536
	ds_write_b16 v112, v95 offset:1600
	ds_write_b16 v112, v101 offset:1664
	ds_write_b16 v112, v107 offset:1728
	ds_read_b128 v[120:123], v113
	ds_read_b128 v[124:127], v113 offset:1024
	s_waitcnt lgkmcnt(0)
	global_store_dwordx4 v114, v[120:123], s[98:99]
	s_add_u32 s98, s98, 0x16000
	s_addc_u32 s99, s99, 0
	global_store_dwordx4 v114, v[124:127], s[98:99]
	s_add_u32 s98, s98, 0x16000
	s_addc_u32 s99, s99, 0
	s_add_i32 s47, s47, s92
	s_cmpk_gt_i32 s47, 0x107f
	s_cbranch_scc1 .LBB0_2292
